# NSA compress-MLP output loop rewritten by hand: lane=channel, 16-k blocks of w2 kept 3 deep in flight, hidden-row values broadcast with DPP row_newbcast fmac (f32 fma chain in k order)
# speedup vs baseline: 1.0773x; 1.0089x over previous
.LBB0_709:
	s_ashr_i32 s15, s14, 31
	s_lshl_b64 s[4:5], s[14:15], 9
	s_add_u32 s6, s20, s4
	s_addc_u32 s7, s21, s5
	s_ashr_i32 s4, s2, 10
	v_readlane_b32 s5, v242, 19
	s_add_i32 s4, s4, s5
	s_ashr_i32 s5, s4, 31
	s_lshl_b64 s[4:5], s[4:5], 16
	v_mov_b32_e32 v4, 0
	v_lshl_add_u64 v[14:15], v[12:13], 0, s[4:5]
	s_mov_b32 s15, -8
	v_mov_b32_e32 v5, v4
	v_mov_b32_e32 v2, v4
	v_mov_b32_e32 v3, v4
	v_lshlrev_b32_e32 v16, 1, v22
	global_load_ushort v116, v16, s[6:7] offset:-1552
	global_load_ushort v117, v16, s[6:7] offset:-1040
	global_load_ushort v118, v16, s[6:7] offset:-528
	global_load_ushort v119, v16, s[6:7] offset:-16
	global_load_dword v26, v[14:15], off offset:-2048
	global_load_dword v27, v[14:15], off offset:-1792
	global_load_dword v28, v[14:15], off offset:-1536
	global_load_dword v29, v[14:15], off offset:-1280
	global_load_dword v30, v[14:15], off offset:-1024
	global_load_dword v31, v[14:15], off offset:-768
	global_load_dword v32, v[14:15], off offset:-512
	global_load_dword v33, v[14:15], off offset:-256
	global_load_dword v34, v[14:15], off offset:0
	global_load_dword v35, v[14:15], off offset:256
	global_load_dword v36, v[14:15], off offset:512
	global_load_dword v37, v[14:15], off offset:768
	global_load_dword v38, v[14:15], off offset:1024
	global_load_dword v39, v[14:15], off offset:1280
	global_load_dword v40, v[14:15], off offset:1536
	global_load_dword v41, v[14:15], off offset:1792
	v_lshl_add_u64 v[14:15], v[14:15], 0, s[58:59]
	v_add_u32_e32 v16, 32, v16
	global_load_ushort v120, v16, s[6:7] offset:-1552
	global_load_ushort v121, v16, s[6:7] offset:-1040
	global_load_ushort v122, v16, s[6:7] offset:-528
	global_load_ushort v123, v16, s[6:7] offset:-16
	global_load_dword v42, v[14:15], off offset:-2048
	global_load_dword v43, v[14:15], off offset:-1792
	global_load_dword v44, v[14:15], off offset:-1536
	global_load_dword v45, v[14:15], off offset:-1280
	global_load_dword v46, v[14:15], off offset:-1024
	global_load_dword v47, v[14:15], off offset:-768
	global_load_dword v48, v[14:15], off offset:-512
	global_load_dword v49, v[14:15], off offset:-256
	global_load_dword v50, v[14:15], off offset:0
	global_load_dword v51, v[14:15], off offset:256
	global_load_dword v52, v[14:15], off offset:512
	global_load_dword v53, v[14:15], off offset:768
	global_load_dword v54, v[14:15], off offset:1024
	global_load_dword v55, v[14:15], off offset:1280
	global_load_dword v56, v[14:15], off offset:1536
	global_load_dword v57, v[14:15], off offset:1792
	v_lshl_add_u64 v[14:15], v[14:15], 0, s[58:59]
	v_add_u32_e32 v16, 32, v16
	global_load_ushort v124, v16, s[6:7] offset:-1552
	global_load_ushort v125, v16, s[6:7] offset:-1040
	global_load_ushort v126, v16, s[6:7] offset:-528
	global_load_ushort v127, v16, s[6:7] offset:-16
	global_load_dword v58, v[14:15], off offset:-2048
	global_load_dword v59, v[14:15], off offset:-1792
	global_load_dword v60, v[14:15], off offset:-1536
	global_load_dword v61, v[14:15], off offset:-1280
	global_load_dword v62, v[14:15], off offset:-1024
	global_load_dword v63, v[14:15], off offset:-768
	global_load_dword v64, v[14:15], off offset:-512
	global_load_dword v65, v[14:15], off offset:-256
	global_load_dword v66, v[14:15], off offset:0
	global_load_dword v67, v[14:15], off offset:256
	global_load_dword v68, v[14:15], off offset:512
	global_load_dword v69, v[14:15], off offset:768
	global_load_dword v70, v[14:15], off offset:1024
	global_load_dword v71, v[14:15], off offset:1280
	global_load_dword v72, v[14:15], off offset:1536
	global_load_dword v73, v[14:15], off offset:1792
	v_lshl_add_u64 v[14:15], v[14:15], 0, s[58:59]
	v_add_u32_e32 v16, 32, v16
	s_mov_b32 s15, 0
m3c_loop:
	s_waitcnt vmcnt(40)
	global_load_ushort v128, v16, s[6:7] offset:-1552
	global_load_ushort v129, v16, s[6:7] offset:-1040
	global_load_ushort v130, v16, s[6:7] offset:-528
	global_load_ushort v131, v16, s[6:7] offset:-16
	global_load_dword v74, v[14:15], off offset:-2048
	global_load_dword v75, v[14:15], off offset:-1792
	global_load_dword v76, v[14:15], off offset:-1536
	global_load_dword v77, v[14:15], off offset:-1280
	global_load_dword v78, v[14:15], off offset:-1024
	global_load_dword v79, v[14:15], off offset:-768
	global_load_dword v80, v[14:15], off offset:-512
	global_load_dword v81, v[14:15], off offset:-256
	global_load_dword v82, v[14:15], off offset:0
	global_load_dword v83, v[14:15], off offset:256
	global_load_dword v84, v[14:15], off offset:512
	global_load_dword v85, v[14:15], off offset:768
	global_load_dword v86, v[14:15], off offset:1024
	global_load_dword v87, v[14:15], off offset:1280
	global_load_dword v88, v[14:15], off offset:1536
	global_load_dword v89, v[14:15], off offset:1792
	v_lshl_add_u64 v[14:15], v[14:15], 0, s[58:59]
	v_add_u32_e32 v16, 32, v16
	v_lshlrev_b32_e32 v116, 16, v116
	v_lshlrev_b32_e32 v117, 16, v117
	v_lshlrev_b32_e32 v118, 16, v118
	v_lshlrev_b32_e32 v119, 16, v119
	v_fmac_f32_dpp v4, v116, v26 row_newbcast:0 row_mask:0xf bank_mask:0xf
	v_fmac_f32_dpp v5, v117, v26 row_newbcast:0 row_mask:0xf bank_mask:0xf
	v_fmac_f32_dpp v2, v118, v26 row_newbcast:0 row_mask:0xf bank_mask:0xf
	v_fmac_f32_dpp v3, v119, v26 row_newbcast:0 row_mask:0xf bank_mask:0xf
	v_fmac_f32_dpp v4, v116, v27 row_newbcast:1 row_mask:0xf bank_mask:0xf
	v_fmac_f32_dpp v5, v117, v27 row_newbcast:1 row_mask:0xf bank_mask:0xf
	v_fmac_f32_dpp v2, v118, v27 row_newbcast:1 row_mask:0xf bank_mask:0xf
	v_fmac_f32_dpp v3, v119, v27 row_newbcast:1 row_mask:0xf bank_mask:0xf
	v_fmac_f32_dpp v4, v116, v28 row_newbcast:2 row_mask:0xf bank_mask:0xf
	v_fmac_f32_dpp v5, v117, v28 row_newbcast:2 row_mask:0xf bank_mask:0xf
	v_fmac_f32_dpp v2, v118, v28 row_newbcast:2 row_mask:0xf bank_mask:0xf
	v_fmac_f32_dpp v3, v119, v28 row_newbcast:2 row_mask:0xf bank_mask:0xf
	v_fmac_f32_dpp v4, v116, v29 row_newbcast:3 row_mask:0xf bank_mask:0xf
	v_fmac_f32_dpp v5, v117, v29 row_newbcast:3 row_mask:0xf bank_mask:0xf
	v_fmac_f32_dpp v2, v118, v29 row_newbcast:3 row_mask:0xf bank_mask:0xf
	v_fmac_f32_dpp v3, v119, v29 row_newbcast:3 row_mask:0xf bank_mask:0xf
	v_fmac_f32_dpp v4, v116, v30 row_newbcast:4 row_mask:0xf bank_mask:0xf
	v_fmac_f32_dpp v5, v117, v30 row_newbcast:4 row_mask:0xf bank_mask:0xf
	v_fmac_f32_dpp v2, v118, v30 row_newbcast:4 row_mask:0xf bank_mask:0xf
	v_fmac_f32_dpp v3, v119, v30 row_newbcast:4 row_mask:0xf bank_mask:0xf
	v_fmac_f32_dpp v4, v116, v31 row_newbcast:5 row_mask:0xf bank_mask:0xf
	v_fmac_f32_dpp v5, v117, v31 row_newbcast:5 row_mask:0xf bank_mask:0xf
	v_fmac_f32_dpp v2, v118, v31 row_newbcast:5 row_mask:0xf bank_mask:0xf
	v_fmac_f32_dpp v3, v119, v31 row_newbcast:5 row_mask:0xf bank_mask:0xf
	v_fmac_f32_dpp v4, v116, v32 row_newbcast:6 row_mask:0xf bank_mask:0xf
	v_fmac_f32_dpp v5, v117, v32 row_newbcast:6 row_mask:0xf bank_mask:0xf
	v_fmac_f32_dpp v2, v118, v32 row_newbcast:6 row_mask:0xf bank_mask:0xf
	v_fmac_f32_dpp v3, v119, v32 row_newbcast:6 row_mask:0xf bank_mask:0xf
	v_fmac_f32_dpp v4, v116, v33 row_newbcast:7 row_mask:0xf bank_mask:0xf
	v_fmac_f32_dpp v5, v117, v33 row_newbcast:7 row_mask:0xf bank_mask:0xf
	v_fmac_f32_dpp v2, v118, v33 row_newbcast:7 row_mask:0xf bank_mask:0xf
	v_fmac_f32_dpp v3, v119, v33 row_newbcast:7 row_mask:0xf bank_mask:0xf
	v_fmac_f32_dpp v4, v116, v34 row_newbcast:8 row_mask:0xf bank_mask:0xf
	v_fmac_f32_dpp v5, v117, v34 row_newbcast:8 row_mask:0xf bank_mask:0xf
	v_fmac_f32_dpp v2, v118, v34 row_newbcast:8 row_mask:0xf bank_mask:0xf
	v_fmac_f32_dpp v3, v119, v34 row_newbcast:8 row_mask:0xf bank_mask:0xf
	v_fmac_f32_dpp v4, v116, v35 row_newbcast:9 row_mask:0xf bank_mask:0xf
	v_fmac_f32_dpp v5, v117, v35 row_newbcast:9 row_mask:0xf bank_mask:0xf
	v_fmac_f32_dpp v2, v118, v35 row_newbcast:9 row_mask:0xf bank_mask:0xf
	v_fmac_f32_dpp v3, v119, v35 row_newbcast:9 row_mask:0xf bank_mask:0xf
	v_fmac_f32_dpp v4, v116, v36 row_newbcast:10 row_mask:0xf bank_mask:0xf
	v_fmac_f32_dpp v5, v117, v36 row_newbcast:10 row_mask:0xf bank_mask:0xf
	v_fmac_f32_dpp v2, v118, v36 row_newbcast:10 row_mask:0xf bank_mask:0xf
	v_fmac_f32_dpp v3, v119, v36 row_newbcast:10 row_mask:0xf bank_mask:0xf
	v_fmac_f32_dpp v4, v116, v37 row_newbcast:11 row_mask:0xf bank_mask:0xf
	v_fmac_f32_dpp v5, v117, v37 row_newbcast:11 row_mask:0xf bank_mask:0xf
	v_fmac_f32_dpp v2, v118, v37 row_newbcast:11 row_mask:0xf bank_mask:0xf
	v_fmac_f32_dpp v3, v119, v37 row_newbcast:11 row_mask:0xf bank_mask:0xf
	v_fmac_f32_dpp v4, v116, v38 row_newbcast:12 row_mask:0xf bank_mask:0xf
	v_fmac_f32_dpp v5, v117, v38 row_newbcast:12 row_mask:0xf bank_mask:0xf
	v_fmac_f32_dpp v2, v118, v38 row_newbcast:12 row_mask:0xf bank_mask:0xf
	v_fmac_f32_dpp v3, v119, v38 row_newbcast:12 row_mask:0xf bank_mask:0xf
	v_fmac_f32_dpp v4, v116, v39 row_newbcast:13 row_mask:0xf bank_mask:0xf
	v_fmac_f32_dpp v5, v117, v39 row_newbcast:13 row_mask:0xf bank_mask:0xf
	v_fmac_f32_dpp v2, v118, v39 row_newbcast:13 row_mask:0xf bank_mask:0xf
	v_fmac_f32_dpp v3, v119, v39 row_newbcast:13 row_mask:0xf bank_mask:0xf
	v_fmac_f32_dpp v4, v116, v40 row_newbcast:14 row_mask:0xf bank_mask:0xf
	v_fmac_f32_dpp v5, v117, v40 row_newbcast:14 row_mask:0xf bank_mask:0xf
	v_fmac_f32_dpp v2, v118, v40 row_newbcast:14 row_mask:0xf bank_mask:0xf
	v_fmac_f32_dpp v3, v119, v40 row_newbcast:14 row_mask:0xf bank_mask:0xf
	v_fmac_f32_dpp v4, v116, v41 row_newbcast:15 row_mask:0xf bank_mask:0xf
	v_fmac_f32_dpp v5, v117, v41 row_newbcast:15 row_mask:0xf bank_mask:0xf
	v_fmac_f32_dpp v2, v118, v41 row_newbcast:15 row_mask:0xf bank_mask:0xf
	v_fmac_f32_dpp v3, v119, v41 row_newbcast:15 row_mask:0xf bank_mask:0xf
	s_waitcnt vmcnt(40)
	global_load_ushort v116, v16, s[6:7] offset:-1552
	global_load_ushort v117, v16, s[6:7] offset:-1040
	global_load_ushort v118, v16, s[6:7] offset:-528
	global_load_ushort v119, v16, s[6:7] offset:-16
	global_load_dword v26, v[14:15], off offset:-2048
	global_load_dword v27, v[14:15], off offset:-1792
	global_load_dword v28, v[14:15], off offset:-1536
	global_load_dword v29, v[14:15], off offset:-1280
	global_load_dword v30, v[14:15], off offset:-1024
	global_load_dword v31, v[14:15], off offset:-768
	global_load_dword v32, v[14:15], off offset:-512
	global_load_dword v33, v[14:15], off offset:-256
	global_load_dword v34, v[14:15], off offset:0
	global_load_dword v35, v[14:15], off offset:256
	global_load_dword v36, v[14:15], off offset:512
	global_load_dword v37, v[14:15], off offset:768
	global_load_dword v38, v[14:15], off offset:1024
	global_load_dword v39, v[14:15], off offset:1280
	global_load_dword v40, v[14:15], off offset:1536
	global_load_dword v41, v[14:15], off offset:1792
	v_lshl_add_u64 v[14:15], v[14:15], 0, s[58:59]
	v_add_u32_e32 v16, 32, v16
	v_lshlrev_b32_e32 v120, 16, v120
	v_lshlrev_b32_e32 v121, 16, v121
	v_lshlrev_b32_e32 v122, 16, v122
	v_lshlrev_b32_e32 v123, 16, v123
	v_fmac_f32_dpp v4, v120, v42 row_newbcast:0 row_mask:0xf bank_mask:0xf
	v_fmac_f32_dpp v5, v121, v42 row_newbcast:0 row_mask:0xf bank_mask:0xf
	v_fmac_f32_dpp v2, v122, v42 row_newbcast:0 row_mask:0xf bank_mask:0xf
	v_fmac_f32_dpp v3, v123, v42 row_newbcast:0 row_mask:0xf bank_mask:0xf
	v_fmac_f32_dpp v4, v120, v43 row_newbcast:1 row_mask:0xf bank_mask:0xf
	v_fmac_f32_dpp v5, v121, v43 row_newbcast:1 row_mask:0xf bank_mask:0xf
	v_fmac_f32_dpp v2, v122, v43 row_newbcast:1 row_mask:0xf bank_mask:0xf
	v_fmac_f32_dpp v3, v123, v43 row_newbcast:1 row_mask:0xf bank_mask:0xf
	v_fmac_f32_dpp v4, v120, v44 row_newbcast:2 row_mask:0xf bank_mask:0xf
	v_fmac_f32_dpp v5, v121, v44 row_newbcast:2 row_mask:0xf bank_mask:0xf
	v_fmac_f32_dpp v2, v122, v44 row_newbcast:2 row_mask:0xf bank_mask:0xf
	v_fmac_f32_dpp v3, v123, v44 row_newbcast:2 row_mask:0xf bank_mask:0xf
	v_fmac_f32_dpp v4, v120, v45 row_newbcast:3 row_mask:0xf bank_mask:0xf
	v_fmac_f32_dpp v5, v121, v45 row_newbcast:3 row_mask:0xf bank_mask:0xf
	v_fmac_f32_dpp v2, v122, v45 row_newbcast:3 row_mask:0xf bank_mask:0xf
	v_fmac_f32_dpp v3, v123, v45 row_newbcast:3 row_mask:0xf bank_mask:0xf
	v_fmac_f32_dpp v4, v120, v46 row_newbcast:4 row_mask:0xf bank_mask:0xf
	v_fmac_f32_dpp v5, v121, v46 row_newbcast:4 row_mask:0xf bank_mask:0xf
	v_fmac_f32_dpp v2, v122, v46 row_newbcast:4 row_mask:0xf bank_mask:0xf
	v_fmac_f32_dpp v3, v123, v46 row_newbcast:4 row_mask:0xf bank_mask:0xf
	v_fmac_f32_dpp v4, v120, v47 row_newbcast:5 row_mask:0xf bank_mask:0xf
	v_fmac_f32_dpp v5, v121, v47 row_newbcast:5 row_mask:0xf bank_mask:0xf
	v_fmac_f32_dpp v2, v122, v47 row_newbcast:5 row_mask:0xf bank_mask:0xf
	v_fmac_f32_dpp v3, v123, v47 row_newbcast:5 row_mask:0xf bank_mask:0xf
	v_fmac_f32_dpp v4, v120, v48 row_newbcast:6 row_mask:0xf bank_mask:0xf
	v_fmac_f32_dpp v5, v121, v48 row_newbcast:6 row_mask:0xf bank_mask:0xf
	v_fmac_f32_dpp v2, v122, v48 row_newbcast:6 row_mask:0xf bank_mask:0xf
	v_fmac_f32_dpp v3, v123, v48 row_newbcast:6 row_mask:0xf bank_mask:0xf
	v_fmac_f32_dpp v4, v120, v49 row_newbcast:7 row_mask:0xf bank_mask:0xf
	v_fmac_f32_dpp v5, v121, v49 row_newbcast:7 row_mask:0xf bank_mask:0xf
	v_fmac_f32_dpp v2, v122, v49 row_newbcast:7 row_mask:0xf bank_mask:0xf
	v_fmac_f32_dpp v3, v123, v49 row_newbcast:7 row_mask:0xf bank_mask:0xf
	v_fmac_f32_dpp v4, v120, v50 row_newbcast:8 row_mask:0xf bank_mask:0xf
	v_fmac_f32_dpp v5, v121, v50 row_newbcast:8 row_mask:0xf bank_mask:0xf
	v_fmac_f32_dpp v2, v122, v50 row_newbcast:8 row_mask:0xf bank_mask:0xf
	v_fmac_f32_dpp v3, v123, v50 row_newbcast:8 row_mask:0xf bank_mask:0xf
	v_fmac_f32_dpp v4, v120, v51 row_newbcast:9 row_mask:0xf bank_mask:0xf
	v_fmac_f32_dpp v5, v121, v51 row_newbcast:9 row_mask:0xf bank_mask:0xf
	v_fmac_f32_dpp v2, v122, v51 row_newbcast:9 row_mask:0xf bank_mask:0xf
	v_fmac_f32_dpp v3, v123, v51 row_newbcast:9 row_mask:0xf bank_mask:0xf
	v_fmac_f32_dpp v4, v120, v52 row_newbcast:10 row_mask:0xf bank_mask:0xf
	v_fmac_f32_dpp v5, v121, v52 row_newbcast:10 row_mask:0xf bank_mask:0xf
	v_fmac_f32_dpp v2, v122, v52 row_newbcast:10 row_mask:0xf bank_mask:0xf
	v_fmac_f32_dpp v3, v123, v52 row_newbcast:10 row_mask:0xf bank_mask:0xf
	v_fmac_f32_dpp v4, v120, v53 row_newbcast:11 row_mask:0xf bank_mask:0xf
	v_fmac_f32_dpp v5, v121, v53 row_newbcast:11 row_mask:0xf bank_mask:0xf
	v_fmac_f32_dpp v2, v122, v53 row_newbcast:11 row_mask:0xf bank_mask:0xf
	v_fmac_f32_dpp v3, v123, v53 row_newbcast:11 row_mask:0xf bank_mask:0xf
	v_fmac_f32_dpp v4, v120, v54 row_newbcast:12 row_mask:0xf bank_mask:0xf
	v_fmac_f32_dpp v5, v121, v54 row_newbcast:12 row_mask:0xf bank_mask:0xf
	v_fmac_f32_dpp v2, v122, v54 row_newbcast:12 row_mask:0xf bank_mask:0xf
	v_fmac_f32_dpp v3, v123, v54 row_newbcast:12 row_mask:0xf bank_mask:0xf
	v_fmac_f32_dpp v4, v120, v55 row_newbcast:13 row_mask:0xf bank_mask:0xf
	v_fmac_f32_dpp v5, v121, v55 row_newbcast:13 row_mask:0xf bank_mask:0xf
	v_fmac_f32_dpp v2, v122, v55 row_newbcast:13 row_mask:0xf bank_mask:0xf
	v_fmac_f32_dpp v3, v123, v55 row_newbcast:13 row_mask:0xf bank_mask:0xf
	v_fmac_f32_dpp v4, v120, v56 row_newbcast:14 row_mask:0xf bank_mask:0xf
	v_fmac_f32_dpp v5, v121, v56 row_newbcast:14 row_mask:0xf bank_mask:0xf
	v_fmac_f32_dpp v2, v122, v56 row_newbcast:14 row_mask:0xf bank_mask:0xf
	v_fmac_f32_dpp v3, v123, v56 row_newbcast:14 row_mask:0xf bank_mask:0xf
	v_fmac_f32_dpp v4, v120, v57 row_newbcast:15 row_mask:0xf bank_mask:0xf
	v_fmac_f32_dpp v5, v121, v57 row_newbcast:15 row_mask:0xf bank_mask:0xf
	v_fmac_f32_dpp v2, v122, v57 row_newbcast:15 row_mask:0xf bank_mask:0xf
	v_fmac_f32_dpp v3, v123, v57 row_newbcast:15 row_mask:0xf bank_mask:0xf
	s_waitcnt vmcnt(40)
	global_load_ushort v120, v16, s[6:7] offset:-1552
	global_load_ushort v121, v16, s[6:7] offset:-1040
	global_load_ushort v122, v16, s[6:7] offset:-528
	global_load_ushort v123, v16, s[6:7] offset:-16
	global_load_dword v42, v[14:15], off offset:-2048
	global_load_dword v43, v[14:15], off offset:-1792
	global_load_dword v44, v[14:15], off offset:-1536
	global_load_dword v45, v[14:15], off offset:-1280
	global_load_dword v46, v[14:15], off offset:-1024
	global_load_dword v47, v[14:15], off offset:-768
	global_load_dword v48, v[14:15], off offset:-512
	global_load_dword v49, v[14:15], off offset:-256
	global_load_dword v50, v[14:15], off offset:0
	global_load_dword v51, v[14:15], off offset:256
	global_load_dword v52, v[14:15], off offset:512
	global_load_dword v53, v[14:15], off offset:768
	global_load_dword v54, v[14:15], off offset:1024
	global_load_dword v55, v[14:15], off offset:1280
	global_load_dword v56, v[14:15], off offset:1536
	global_load_dword v57, v[14:15], off offset:1792
	v_lshl_add_u64 v[14:15], v[14:15], 0, s[58:59]
	v_add_u32_e32 v16, 32, v16
	v_lshlrev_b32_e32 v124, 16, v124
	v_lshlrev_b32_e32 v125, 16, v125
	v_lshlrev_b32_e32 v126, 16, v126
	v_lshlrev_b32_e32 v127, 16, v127
	v_fmac_f32_dpp v4, v124, v58 row_newbcast:0 row_mask:0xf bank_mask:0xf
	v_fmac_f32_dpp v5, v125, v58 row_newbcast:0 row_mask:0xf bank_mask:0xf
	v_fmac_f32_dpp v2, v126, v58 row_newbcast:0 row_mask:0xf bank_mask:0xf
	v_fmac_f32_dpp v3, v127, v58 row_newbcast:0 row_mask:0xf bank_mask:0xf
	v_fmac_f32_dpp v4, v124, v59 row_newbcast:1 row_mask:0xf bank_mask:0xf
	v_fmac_f32_dpp v5, v125, v59 row_newbcast:1 row_mask:0xf bank_mask:0xf
	v_fmac_f32_dpp v2, v126, v59 row_newbcast:1 row_mask:0xf bank_mask:0xf
	v_fmac_f32_dpp v3, v127, v59 row_newbcast:1 row_mask:0xf bank_mask:0xf
	v_fmac_f32_dpp v4, v124, v60 row_newbcast:2 row_mask:0xf bank_mask:0xf
	v_fmac_f32_dpp v5, v125, v60 row_newbcast:2 row_mask:0xf bank_mask:0xf
	v_fmac_f32_dpp v2, v126, v60 row_newbcast:2 row_mask:0xf bank_mask:0xf
	v_fmac_f32_dpp v3, v127, v60 row_newbcast:2 row_mask:0xf bank_mask:0xf
	v_fmac_f32_dpp v4, v124, v61 row_newbcast:3 row_mask:0xf bank_mask:0xf
	v_fmac_f32_dpp v5, v125, v61 row_newbcast:3 row_mask:0xf bank_mask:0xf
	v_fmac_f32_dpp v2, v126, v61 row_newbcast:3 row_mask:0xf bank_mask:0xf
	v_fmac_f32_dpp v3, v127, v61 row_newbcast:3 row_mask:0xf bank_mask:0xf
	v_fmac_f32_dpp v4, v124, v62 row_newbcast:4 row_mask:0xf bank_mask:0xf
	v_fmac_f32_dpp v5, v125, v62 row_newbcast:4 row_mask:0xf bank_mask:0xf
	v_fmac_f32_dpp v2, v126, v62 row_newbcast:4 row_mask:0xf bank_mask:0xf
	v_fmac_f32_dpp v3, v127, v62 row_newbcast:4 row_mask:0xf bank_mask:0xf
	v_fmac_f32_dpp v4, v124, v63 row_newbcast:5 row_mask:0xf bank_mask:0xf
	v_fmac_f32_dpp v5, v125, v63 row_newbcast:5 row_mask:0xf bank_mask:0xf
	v_fmac_f32_dpp v2, v126, v63 row_newbcast:5 row_mask:0xf bank_mask:0xf
	v_fmac_f32_dpp v3, v127, v63 row_newbcast:5 row_mask:0xf bank_mask:0xf
	v_fmac_f32_dpp v4, v124, v64 row_newbcast:6 row_mask:0xf bank_mask:0xf
	v_fmac_f32_dpp v5, v125, v64 row_newbcast:6 row_mask:0xf bank_mask:0xf
	v_fmac_f32_dpp v2, v126, v64 row_newbcast:6 row_mask:0xf bank_mask:0xf
	v_fmac_f32_dpp v3, v127, v64 row_newbcast:6 row_mask:0xf bank_mask:0xf
	v_fmac_f32_dpp v4, v124, v65 row_newbcast:7 row_mask:0xf bank_mask:0xf
	v_fmac_f32_dpp v5, v125, v65 row_newbcast:7 row_mask:0xf bank_mask:0xf
	v_fmac_f32_dpp v2, v126, v65 row_newbcast:7 row_mask:0xf bank_mask:0xf
	v_fmac_f32_dpp v3, v127, v65 row_newbcast:7 row_mask:0xf bank_mask:0xf
	v_fmac_f32_dpp v4, v124, v66 row_newbcast:8 row_mask:0xf bank_mask:0xf
	v_fmac_f32_dpp v5, v125, v66 row_newbcast:8 row_mask:0xf bank_mask:0xf
	v_fmac_f32_dpp v2, v126, v66 row_newbcast:8 row_mask:0xf bank_mask:0xf
	v_fmac_f32_dpp v3, v127, v66 row_newbcast:8 row_mask:0xf bank_mask:0xf
	v_fmac_f32_dpp v4, v124, v67 row_newbcast:9 row_mask:0xf bank_mask:0xf
	v_fmac_f32_dpp v5, v125, v67 row_newbcast:9 row_mask:0xf bank_mask:0xf
	v_fmac_f32_dpp v2, v126, v67 row_newbcast:9 row_mask:0xf bank_mask:0xf
	v_fmac_f32_dpp v3, v127, v67 row_newbcast:9 row_mask:0xf bank_mask:0xf
	v_fmac_f32_dpp v4, v124, v68 row_newbcast:10 row_mask:0xf bank_mask:0xf
	v_fmac_f32_dpp v5, v125, v68 row_newbcast:10 row_mask:0xf bank_mask:0xf
	v_fmac_f32_dpp v2, v126, v68 row_newbcast:10 row_mask:0xf bank_mask:0xf
	v_fmac_f32_dpp v3, v127, v68 row_newbcast:10 row_mask:0xf bank_mask:0xf
	v_fmac_f32_dpp v4, v124, v69 row_newbcast:11 row_mask:0xf bank_mask:0xf
	v_fmac_f32_dpp v5, v125, v69 row_newbcast:11 row_mask:0xf bank_mask:0xf
	v_fmac_f32_dpp v2, v126, v69 row_newbcast:11 row_mask:0xf bank_mask:0xf
	v_fmac_f32_dpp v3, v127, v69 row_newbcast:11 row_mask:0xf bank_mask:0xf
	v_fmac_f32_dpp v4, v124, v70 row_newbcast:12 row_mask:0xf bank_mask:0xf
	v_fmac_f32_dpp v5, v125, v70 row_newbcast:12 row_mask:0xf bank_mask:0xf
	v_fmac_f32_dpp v2, v126, v70 row_newbcast:12 row_mask:0xf bank_mask:0xf
	v_fmac_f32_dpp v3, v127, v70 row_newbcast:12 row_mask:0xf bank_mask:0xf
	v_fmac_f32_dpp v4, v124, v71 row_newbcast:13 row_mask:0xf bank_mask:0xf
	v_fmac_f32_dpp v5, v125, v71 row_newbcast:13 row_mask:0xf bank_mask:0xf
	v_fmac_f32_dpp v2, v126, v71 row_newbcast:13 row_mask:0xf bank_mask:0xf
	v_fmac_f32_dpp v3, v127, v71 row_newbcast:13 row_mask:0xf bank_mask:0xf
	v_fmac_f32_dpp v4, v124, v72 row_newbcast:14 row_mask:0xf bank_mask:0xf
	v_fmac_f32_dpp v5, v125, v72 row_newbcast:14 row_mask:0xf bank_mask:0xf
	v_fmac_f32_dpp v2, v126, v72 row_newbcast:14 row_mask:0xf bank_mask:0xf
	v_fmac_f32_dpp v3, v127, v72 row_newbcast:14 row_mask:0xf bank_mask:0xf
	v_fmac_f32_dpp v4, v124, v73 row_newbcast:15 row_mask:0xf bank_mask:0xf
	v_fmac_f32_dpp v5, v125, v73 row_newbcast:15 row_mask:0xf bank_mask:0xf
	v_fmac_f32_dpp v2, v126, v73 row_newbcast:15 row_mask:0xf bank_mask:0xf
	v_fmac_f32_dpp v3, v127, v73 row_newbcast:15 row_mask:0xf bank_mask:0xf
	s_waitcnt vmcnt(40)
	global_load_ushort v124, v16, s[6:7] offset:-1552
	global_load_ushort v125, v16, s[6:7] offset:-1040
	global_load_ushort v126, v16, s[6:7] offset:-528
	global_load_ushort v127, v16, s[6:7] offset:-16
	global_load_dword v58, v[14:15], off offset:-2048
	global_load_dword v59, v[14:15], off offset:-1792
	global_load_dword v60, v[14:15], off offset:-1536
	global_load_dword v61, v[14:15], off offset:-1280
	global_load_dword v62, v[14:15], off offset:-1024
	global_load_dword v63, v[14:15], off offset:-768
	global_load_dword v64, v[14:15], off offset:-512
	global_load_dword v65, v[14:15], off offset:-256
	global_load_dword v66, v[14:15], off offset:0
	global_load_dword v67, v[14:15], off offset:256
	global_load_dword v68, v[14:15], off offset:512
	global_load_dword v69, v[14:15], off offset:768
	global_load_dword v70, v[14:15], off offset:1024
	global_load_dword v71, v[14:15], off offset:1280
	global_load_dword v72, v[14:15], off offset:1536
	global_load_dword v73, v[14:15], off offset:1792
	v_lshl_add_u64 v[14:15], v[14:15], 0, s[58:59]
	v_add_u32_e32 v16, 32, v16
	v_lshlrev_b32_e32 v128, 16, v128
	v_lshlrev_b32_e32 v129, 16, v129
	v_lshlrev_b32_e32 v130, 16, v130
	v_lshlrev_b32_e32 v131, 16, v131
	v_fmac_f32_dpp v4, v128, v74 row_newbcast:0 row_mask:0xf bank_mask:0xf
	v_fmac_f32_dpp v5, v129, v74 row_newbcast:0 row_mask:0xf bank_mask:0xf
	v_fmac_f32_dpp v2, v130, v74 row_newbcast:0 row_mask:0xf bank_mask:0xf
	v_fmac_f32_dpp v3, v131, v74 row_newbcast:0 row_mask:0xf bank_mask:0xf
	v_fmac_f32_dpp v4, v128, v75 row_newbcast:1 row_mask:0xf bank_mask:0xf
	v_fmac_f32_dpp v5, v129, v75 row_newbcast:1 row_mask:0xf bank_mask:0xf
	v_fmac_f32_dpp v2, v130, v75 row_newbcast:1 row_mask:0xf bank_mask:0xf
	v_fmac_f32_dpp v3, v131, v75 row_newbcast:1 row_mask:0xf bank_mask:0xf
	v_fmac_f32_dpp v4, v128, v76 row_newbcast:2 row_mask:0xf bank_mask:0xf
	v_fmac_f32_dpp v5, v129, v76 row_newbcast:2 row_mask:0xf bank_mask:0xf
	v_fmac_f32_dpp v2, v130, v76 row_newbcast:2 row_mask:0xf bank_mask:0xf
	v_fmac_f32_dpp v3, v131, v76 row_newbcast:2 row_mask:0xf bank_mask:0xf
	v_fmac_f32_dpp v4, v128, v77 row_newbcast:3 row_mask:0xf bank_mask:0xf
	v_fmac_f32_dpp v5, v129, v77 row_newbcast:3 row_mask:0xf bank_mask:0xf
	v_fmac_f32_dpp v2, v130, v77 row_newbcast:3 row_mask:0xf bank_mask:0xf
	v_fmac_f32_dpp v3, v131, v77 row_newbcast:3 row_mask:0xf bank_mask:0xf
	v_fmac_f32_dpp v4, v128, v78 row_newbcast:4 row_mask:0xf bank_mask:0xf
	v_fmac_f32_dpp v5, v129, v78 row_newbcast:4 row_mask:0xf bank_mask:0xf
	v_fmac_f32_dpp v2, v130, v78 row_newbcast:4 row_mask:0xf bank_mask:0xf
	v_fmac_f32_dpp v3, v131, v78 row_newbcast:4 row_mask:0xf bank_mask:0xf
	v_fmac_f32_dpp v4, v128, v79 row_newbcast:5 row_mask:0xf bank_mask:0xf
	v_fmac_f32_dpp v5, v129, v79 row_newbcast:5 row_mask:0xf bank_mask:0xf
	v_fmac_f32_dpp v2, v130, v79 row_newbcast:5 row_mask:0xf bank_mask:0xf
	v_fmac_f32_dpp v3, v131, v79 row_newbcast:5 row_mask:0xf bank_mask:0xf
	v_fmac_f32_dpp v4, v128, v80 row_newbcast:6 row_mask:0xf bank_mask:0xf
	v_fmac_f32_dpp v5, v129, v80 row_newbcast:6 row_mask:0xf bank_mask:0xf
	v_fmac_f32_dpp v2, v130, v80 row_newbcast:6 row_mask:0xf bank_mask:0xf
	v_fmac_f32_dpp v3, v131, v80 row_newbcast:6 row_mask:0xf bank_mask:0xf
	v_fmac_f32_dpp v4, v128, v81 row_newbcast:7 row_mask:0xf bank_mask:0xf
	v_fmac_f32_dpp v5, v129, v81 row_newbcast:7 row_mask:0xf bank_mask:0xf
	v_fmac_f32_dpp v2, v130, v81 row_newbcast:7 row_mask:0xf bank_mask:0xf
	v_fmac_f32_dpp v3, v131, v81 row_newbcast:7 row_mask:0xf bank_mask:0xf
	v_fmac_f32_dpp v4, v128, v82 row_newbcast:8 row_mask:0xf bank_mask:0xf
	v_fmac_f32_dpp v5, v129, v82 row_newbcast:8 row_mask:0xf bank_mask:0xf
	v_fmac_f32_dpp v2, v130, v82 row_newbcast:8 row_mask:0xf bank_mask:0xf
	v_fmac_f32_dpp v3, v131, v82 row_newbcast:8 row_mask:0xf bank_mask:0xf
	v_fmac_f32_dpp v4, v128, v83 row_newbcast:9 row_mask:0xf bank_mask:0xf
	v_fmac_f32_dpp v5, v129, v83 row_newbcast:9 row_mask:0xf bank_mask:0xf
	v_fmac_f32_dpp v2, v130, v83 row_newbcast:9 row_mask:0xf bank_mask:0xf
	v_fmac_f32_dpp v3, v131, v83 row_newbcast:9 row_mask:0xf bank_mask:0xf
	v_fmac_f32_dpp v4, v128, v84 row_newbcast:10 row_mask:0xf bank_mask:0xf
	v_fmac_f32_dpp v5, v129, v84 row_newbcast:10 row_mask:0xf bank_mask:0xf
	v_fmac_f32_dpp v2, v130, v84 row_newbcast:10 row_mask:0xf bank_mask:0xf
	v_fmac_f32_dpp v3, v131, v84 row_newbcast:10 row_mask:0xf bank_mask:0xf
	v_fmac_f32_dpp v4, v128, v85 row_newbcast:11 row_mask:0xf bank_mask:0xf
	v_fmac_f32_dpp v5, v129, v85 row_newbcast:11 row_mask:0xf bank_mask:0xf
	v_fmac_f32_dpp v2, v130, v85 row_newbcast:11 row_mask:0xf bank_mask:0xf
	v_fmac_f32_dpp v3, v131, v85 row_newbcast:11 row_mask:0xf bank_mask:0xf
	v_fmac_f32_dpp v4, v128, v86 row_newbcast:12 row_mask:0xf bank_mask:0xf
	v_fmac_f32_dpp v5, v129, v86 row_newbcast:12 row_mask:0xf bank_mask:0xf
	v_fmac_f32_dpp v2, v130, v86 row_newbcast:12 row_mask:0xf bank_mask:0xf
	v_fmac_f32_dpp v3, v131, v86 row_newbcast:12 row_mask:0xf bank_mask:0xf
	v_fmac_f32_dpp v4, v128, v87 row_newbcast:13 row_mask:0xf bank_mask:0xf
	v_fmac_f32_dpp v5, v129, v87 row_newbcast:13 row_mask:0xf bank_mask:0xf
	v_fmac_f32_dpp v2, v130, v87 row_newbcast:13 row_mask:0xf bank_mask:0xf
	v_fmac_f32_dpp v3, v131, v87 row_newbcast:13 row_mask:0xf bank_mask:0xf
	v_fmac_f32_dpp v4, v128, v88 row_newbcast:14 row_mask:0xf bank_mask:0xf
	v_fmac_f32_dpp v5, v129, v88 row_newbcast:14 row_mask:0xf bank_mask:0xf
	v_fmac_f32_dpp v2, v130, v88 row_newbcast:14 row_mask:0xf bank_mask:0xf
	v_fmac_f32_dpp v3, v131, v88 row_newbcast:14 row_mask:0xf bank_mask:0xf
	v_fmac_f32_dpp v4, v128, v89 row_newbcast:15 row_mask:0xf bank_mask:0xf
	v_fmac_f32_dpp v5, v129, v89 row_newbcast:15 row_mask:0xf bank_mask:0xf
	v_fmac_f32_dpp v2, v130, v89 row_newbcast:15 row_mask:0xf bank_mask:0xf
	v_fmac_f32_dpp v3, v131, v89 row_newbcast:15 row_mask:0xf bank_mask:0xf
	s_add_i32 s15, s15, 1
	s_cmp_lt_u32 s15, 3
	s_cbranch_scc1 m3c_loop
	s_waitcnt vmcnt(40)
	global_load_ushort v128, v16, s[6:7] offset:-1552
	global_load_ushort v129, v16, s[6:7] offset:-1040
	global_load_ushort v130, v16, s[6:7] offset:-528
	global_load_ushort v131, v16, s[6:7] offset:-16
	global_load_dword v74, v[14:15], off offset:-2048
	global_load_dword v75, v[14:15], off offset:-1792
	global_load_dword v76, v[14:15], off offset:-1536
	global_load_dword v77, v[14:15], off offset:-1280
	global_load_dword v78, v[14:15], off offset:-1024
	global_load_dword v79, v[14:15], off offset:-768
	global_load_dword v80, v[14:15], off offset:-512
	global_load_dword v81, v[14:15], off offset:-256
	global_load_dword v82, v[14:15], off offset:0
	global_load_dword v83, v[14:15], off offset:256
	global_load_dword v84, v[14:15], off offset:512
	global_load_dword v85, v[14:15], off offset:768
	global_load_dword v86, v[14:15], off offset:1024
	global_load_dword v87, v[14:15], off offset:1280
	global_load_dword v88, v[14:15], off offset:1536
	global_load_dword v89, v[14:15], off offset:1792
	v_lshl_add_u64 v[14:15], v[14:15], 0, s[58:59]
	v_add_u32_e32 v16, 32, v16
	v_lshlrev_b32_e32 v116, 16, v116
	v_lshlrev_b32_e32 v117, 16, v117
	v_lshlrev_b32_e32 v118, 16, v118
	v_lshlrev_b32_e32 v119, 16, v119
	v_fmac_f32_dpp v4, v116, v26 row_newbcast:0 row_mask:0xf bank_mask:0xf
	v_fmac_f32_dpp v5, v117, v26 row_newbcast:0 row_mask:0xf bank_mask:0xf
	v_fmac_f32_dpp v2, v118, v26 row_newbcast:0 row_mask:0xf bank_mask:0xf
	v_fmac_f32_dpp v3, v119, v26 row_newbcast:0 row_mask:0xf bank_mask:0xf
	v_fmac_f32_dpp v4, v116, v27 row_newbcast:1 row_mask:0xf bank_mask:0xf
	v_fmac_f32_dpp v5, v117, v27 row_newbcast:1 row_mask:0xf bank_mask:0xf
	v_fmac_f32_dpp v2, v118, v27 row_newbcast:1 row_mask:0xf bank_mask:0xf
	v_fmac_f32_dpp v3, v119, v27 row_newbcast:1 row_mask:0xf bank_mask:0xf
	v_fmac_f32_dpp v4, v116, v28 row_newbcast:2 row_mask:0xf bank_mask:0xf
	v_fmac_f32_dpp v5, v117, v28 row_newbcast:2 row_mask:0xf bank_mask:0xf
	v_fmac_f32_dpp v2, v118, v28 row_newbcast:2 row_mask:0xf bank_mask:0xf
	v_fmac_f32_dpp v3, v119, v28 row_newbcast:2 row_mask:0xf bank_mask:0xf
	v_fmac_f32_dpp v4, v116, v29 row_newbcast:3 row_mask:0xf bank_mask:0xf
	v_fmac_f32_dpp v5, v117, v29 row_newbcast:3 row_mask:0xf bank_mask:0xf
	v_fmac_f32_dpp v2, v118, v29 row_newbcast:3 row_mask:0xf bank_mask:0xf
	v_fmac_f32_dpp v3, v119, v29 row_newbcast:3 row_mask:0xf bank_mask:0xf
	v_fmac_f32_dpp v4, v116, v30 row_newbcast:4 row_mask:0xf bank_mask:0xf
	v_fmac_f32_dpp v5, v117, v30 row_newbcast:4 row_mask:0xf bank_mask:0xf
	v_fmac_f32_dpp v2, v118, v30 row_newbcast:4 row_mask:0xf bank_mask:0xf
	v_fmac_f32_dpp v3, v119, v30 row_newbcast:4 row_mask:0xf bank_mask:0xf
	v_fmac_f32_dpp v4, v116, v31 row_newbcast:5 row_mask:0xf bank_mask:0xf
	v_fmac_f32_dpp v5, v117, v31 row_newbcast:5 row_mask:0xf bank_mask:0xf
	v_fmac_f32_dpp v2, v118, v31 row_newbcast:5 row_mask:0xf bank_mask:0xf
	v_fmac_f32_dpp v3, v119, v31 row_newbcast:5 row_mask:0xf bank_mask:0xf
	v_fmac_f32_dpp v4, v116, v32 row_newbcast:6 row_mask:0xf bank_mask:0xf
	v_fmac_f32_dpp v5, v117, v32 row_newbcast:6 row_mask:0xf bank_mask:0xf
	v_fmac_f32_dpp v2, v118, v32 row_newbcast:6 row_mask:0xf bank_mask:0xf
	v_fmac_f32_dpp v3, v119, v32 row_newbcast:6 row_mask:0xf bank_mask:0xf
	v_fmac_f32_dpp v4, v116, v33 row_newbcast:7 row_mask:0xf bank_mask:0xf
	v_fmac_f32_dpp v5, v117, v33 row_newbcast:7 row_mask:0xf bank_mask:0xf
	v_fmac_f32_dpp v2, v118, v33 row_newbcast:7 row_mask:0xf bank_mask:0xf
	v_fmac_f32_dpp v3, v119, v33 row_newbcast:7 row_mask:0xf bank_mask:0xf
	v_fmac_f32_dpp v4, v116, v34 row_newbcast:8 row_mask:0xf bank_mask:0xf
	v_fmac_f32_dpp v5, v117, v34 row_newbcast:8 row_mask:0xf bank_mask:0xf
	v_fmac_f32_dpp v2, v118, v34 row_newbcast:8 row_mask:0xf bank_mask:0xf
	v_fmac_f32_dpp v3, v119, v34 row_newbcast:8 row_mask:0xf bank_mask:0xf
	v_fmac_f32_dpp v4, v116, v35 row_newbcast:9 row_mask:0xf bank_mask:0xf
	v_fmac_f32_dpp v5, v117, v35 row_newbcast:9 row_mask:0xf bank_mask:0xf
	v_fmac_f32_dpp v2, v118, v35 row_newbcast:9 row_mask:0xf bank_mask:0xf
	v_fmac_f32_dpp v3, v119, v35 row_newbcast:9 row_mask:0xf bank_mask:0xf
	v_fmac_f32_dpp v4, v116, v36 row_newbcast:10 row_mask:0xf bank_mask:0xf
	v_fmac_f32_dpp v5, v117, v36 row_newbcast:10 row_mask:0xf bank_mask:0xf
	v_fmac_f32_dpp v2, v118, v36 row_newbcast:10 row_mask:0xf bank_mask:0xf
	v_fmac_f32_dpp v3, v119, v36 row_newbcast:10 row_mask:0xf bank_mask:0xf
	v_fmac_f32_dpp v4, v116, v37 row_newbcast:11 row_mask:0xf bank_mask:0xf
	v_fmac_f32_dpp v5, v117, v37 row_newbcast:11 row_mask:0xf bank_mask:0xf
	v_fmac_f32_dpp v2, v118, v37 row_newbcast:11 row_mask:0xf bank_mask:0xf
	v_fmac_f32_dpp v3, v119, v37 row_newbcast:11 row_mask:0xf bank_mask:0xf
	v_fmac_f32_dpp v4, v116, v38 row_newbcast:12 row_mask:0xf bank_mask:0xf
	v_fmac_f32_dpp v5, v117, v38 row_newbcast:12 row_mask:0xf bank_mask:0xf
	v_fmac_f32_dpp v2, v118, v38 row_newbcast:12 row_mask:0xf bank_mask:0xf
	v_fmac_f32_dpp v3, v119, v38 row_newbcast:12 row_mask:0xf bank_mask:0xf
	v_fmac_f32_dpp v4, v116, v39 row_newbcast:13 row_mask:0xf bank_mask:0xf
	v_fmac_f32_dpp v5, v117, v39 row_newbcast:13 row_mask:0xf bank_mask:0xf
	v_fmac_f32_dpp v2, v118, v39 row_newbcast:13 row_mask:0xf bank_mask:0xf
	v_fmac_f32_dpp v3, v119, v39 row_newbcast:13 row_mask:0xf bank_mask:0xf
	v_fmac_f32_dpp v4, v116, v40 row_newbcast:14 row_mask:0xf bank_mask:0xf
	v_fmac_f32_dpp v5, v117, v40 row_newbcast:14 row_mask:0xf bank_mask:0xf
	v_fmac_f32_dpp v2, v118, v40 row_newbcast:14 row_mask:0xf bank_mask:0xf
	v_fmac_f32_dpp v3, v119, v40 row_newbcast:14 row_mask:0xf bank_mask:0xf
	v_fmac_f32_dpp v4, v116, v41 row_newbcast:15 row_mask:0xf bank_mask:0xf
	v_fmac_f32_dpp v5, v117, v41 row_newbcast:15 row_mask:0xf bank_mask:0xf
	v_fmac_f32_dpp v2, v118, v41 row_newbcast:15 row_mask:0xf bank_mask:0xf
	v_fmac_f32_dpp v3, v119, v41 row_newbcast:15 row_mask:0xf bank_mask:0xf
	s_waitcnt vmcnt(40)
	v_lshlrev_b32_e32 v120, 16, v120
	v_lshlrev_b32_e32 v121, 16, v121
	v_lshlrev_b32_e32 v122, 16, v122
	v_lshlrev_b32_e32 v123, 16, v123
	v_fmac_f32_dpp v4, v120, v42 row_newbcast:0 row_mask:0xf bank_mask:0xf
	v_fmac_f32_dpp v5, v121, v42 row_newbcast:0 row_mask:0xf bank_mask:0xf
	v_fmac_f32_dpp v2, v122, v42 row_newbcast:0 row_mask:0xf bank_mask:0xf
	v_fmac_f32_dpp v3, v123, v42 row_newbcast:0 row_mask:0xf bank_mask:0xf
	v_fmac_f32_dpp v4, v120, v43 row_newbcast:1 row_mask:0xf bank_mask:0xf
	v_fmac_f32_dpp v5, v121, v43 row_newbcast:1 row_mask:0xf bank_mask:0xf
	v_fmac_f32_dpp v2, v122, v43 row_newbcast:1 row_mask:0xf bank_mask:0xf
	v_fmac_f32_dpp v3, v123, v43 row_newbcast:1 row_mask:0xf bank_mask:0xf
	v_fmac_f32_dpp v4, v120, v44 row_newbcast:2 row_mask:0xf bank_mask:0xf
	v_fmac_f32_dpp v5, v121, v44 row_newbcast:2 row_mask:0xf bank_mask:0xf
	v_fmac_f32_dpp v2, v122, v44 row_newbcast:2 row_mask:0xf bank_mask:0xf
	v_fmac_f32_dpp v3, v123, v44 row_newbcast:2 row_mask:0xf bank_mask:0xf
	v_fmac_f32_dpp v4, v120, v45 row_newbcast:3 row_mask:0xf bank_mask:0xf
	v_fmac_f32_dpp v5, v121, v45 row_newbcast:3 row_mask:0xf bank_mask:0xf
	v_fmac_f32_dpp v2, v122, v45 row_newbcast:3 row_mask:0xf bank_mask:0xf
	v_fmac_f32_dpp v3, v123, v45 row_newbcast:3 row_mask:0xf bank_mask:0xf
	v_fmac_f32_dpp v4, v120, v46 row_newbcast:4 row_mask:0xf bank_mask:0xf
	v_fmac_f32_dpp v5, v121, v46 row_newbcast:4 row_mask:0xf bank_mask:0xf
	v_fmac_f32_dpp v2, v122, v46 row_newbcast:4 row_mask:0xf bank_mask:0xf
	v_fmac_f32_dpp v3, v123, v46 row_newbcast:4 row_mask:0xf bank_mask:0xf
	v_fmac_f32_dpp v4, v120, v47 row_newbcast:5 row_mask:0xf bank_mask:0xf
	v_fmac_f32_dpp v5, v121, v47 row_newbcast:5 row_mask:0xf bank_mask:0xf
	v_fmac_f32_dpp v2, v122, v47 row_newbcast:5 row_mask:0xf bank_mask:0xf
	v_fmac_f32_dpp v3, v123, v47 row_newbcast:5 row_mask:0xf bank_mask:0xf
	v_fmac_f32_dpp v4, v120, v48 row_newbcast:6 row_mask:0xf bank_mask:0xf
	v_fmac_f32_dpp v5, v121, v48 row_newbcast:6 row_mask:0xf bank_mask:0xf
	v_fmac_f32_dpp v2, v122, v48 row_newbcast:6 row_mask:0xf bank_mask:0xf
	v_fmac_f32_dpp v3, v123, v48 row_newbcast:6 row_mask:0xf bank_mask:0xf
	v_fmac_f32_dpp v4, v120, v49 row_newbcast:7 row_mask:0xf bank_mask:0xf
	v_fmac_f32_dpp v5, v121, v49 row_newbcast:7 row_mask:0xf bank_mask:0xf
	v_fmac_f32_dpp v2, v122, v49 row_newbcast:7 row_mask:0xf bank_mask:0xf
	v_fmac_f32_dpp v3, v123, v49 row_newbcast:7 row_mask:0xf bank_mask:0xf
	v_fmac_f32_dpp v4, v120, v50 row_newbcast:8 row_mask:0xf bank_mask:0xf
	v_fmac_f32_dpp v5, v121, v50 row_newbcast:8 row_mask:0xf bank_mask:0xf
	v_fmac_f32_dpp v2, v122, v50 row_newbcast:8 row_mask:0xf bank_mask:0xf
	v_fmac_f32_dpp v3, v123, v50 row_newbcast:8 row_mask:0xf bank_mask:0xf
	v_fmac_f32_dpp v4, v120, v51 row_newbcast:9 row_mask:0xf bank_mask:0xf
	v_fmac_f32_dpp v5, v121, v51 row_newbcast:9 row_mask:0xf bank_mask:0xf
	v_fmac_f32_dpp v2, v122, v51 row_newbcast:9 row_mask:0xf bank_mask:0xf
	v_fmac_f32_dpp v3, v123, v51 row_newbcast:9 row_mask:0xf bank_mask:0xf
	v_fmac_f32_dpp v4, v120, v52 row_newbcast:10 row_mask:0xf bank_mask:0xf
	v_fmac_f32_dpp v5, v121, v52 row_newbcast:10 row_mask:0xf bank_mask:0xf
	v_fmac_f32_dpp v2, v122, v52 row_newbcast:10 row_mask:0xf bank_mask:0xf
	v_fmac_f32_dpp v3, v123, v52 row_newbcast:10 row_mask:0xf bank_mask:0xf
	v_fmac_f32_dpp v4, v120, v53 row_newbcast:11 row_mask:0xf bank_mask:0xf
	v_fmac_f32_dpp v5, v121, v53 row_newbcast:11 row_mask:0xf bank_mask:0xf
	v_fmac_f32_dpp v2, v122, v53 row_newbcast:11 row_mask:0xf bank_mask:0xf
	v_fmac_f32_dpp v3, v123, v53 row_newbcast:11 row_mask:0xf bank_mask:0xf
	v_fmac_f32_dpp v4, v120, v54 row_newbcast:12 row_mask:0xf bank_mask:0xf
	v_fmac_f32_dpp v5, v121, v54 row_newbcast:12 row_mask:0xf bank_mask:0xf
	v_fmac_f32_dpp v2, v122, v54 row_newbcast:12 row_mask:0xf bank_mask:0xf
	v_fmac_f32_dpp v3, v123, v54 row_newbcast:12 row_mask:0xf bank_mask:0xf
	v_fmac_f32_dpp v4, v120, v55 row_newbcast:13 row_mask:0xf bank_mask:0xf
	v_fmac_f32_dpp v5, v121, v55 row_newbcast:13 row_mask:0xf bank_mask:0xf
	v_fmac_f32_dpp v2, v122, v55 row_newbcast:13 row_mask:0xf bank_mask:0xf
	v_fmac_f32_dpp v3, v123, v55 row_newbcast:13 row_mask:0xf bank_mask:0xf
	v_fmac_f32_dpp v4, v120, v56 row_newbcast:14 row_mask:0xf bank_mask:0xf
	v_fmac_f32_dpp v5, v121, v56 row_newbcast:14 row_mask:0xf bank_mask:0xf
	v_fmac_f32_dpp v2, v122, v56 row_newbcast:14 row_mask:0xf bank_mask:0xf
	v_fmac_f32_dpp v3, v123, v56 row_newbcast:14 row_mask:0xf bank_mask:0xf
	v_fmac_f32_dpp v4, v120, v57 row_newbcast:15 row_mask:0xf bank_mask:0xf
	v_fmac_f32_dpp v5, v121, v57 row_newbcast:15 row_mask:0xf bank_mask:0xf
	v_fmac_f32_dpp v2, v122, v57 row_newbcast:15 row_mask:0xf bank_mask:0xf
	v_fmac_f32_dpp v3, v123, v57 row_newbcast:15 row_mask:0xf bank_mask:0xf
	s_waitcnt vmcnt(20)
	v_lshlrev_b32_e32 v124, 16, v124
	v_lshlrev_b32_e32 v125, 16, v125
	v_lshlrev_b32_e32 v126, 16, v126
	v_lshlrev_b32_e32 v127, 16, v127
	v_fmac_f32_dpp v4, v124, v58 row_newbcast:0 row_mask:0xf bank_mask:0xf
	v_fmac_f32_dpp v5, v125, v58 row_newbcast:0 row_mask:0xf bank_mask:0xf
	v_fmac_f32_dpp v2, v126, v58 row_newbcast:0 row_mask:0xf bank_mask:0xf
	v_fmac_f32_dpp v3, v127, v58 row_newbcast:0 row_mask:0xf bank_mask:0xf
	v_fmac_f32_dpp v4, v124, v59 row_newbcast:1 row_mask:0xf bank_mask:0xf
	v_fmac_f32_dpp v5, v125, v59 row_newbcast:1 row_mask:0xf bank_mask:0xf
	v_fmac_f32_dpp v2, v126, v59 row_newbcast:1 row_mask:0xf bank_mask:0xf
	v_fmac_f32_dpp v3, v127, v59 row_newbcast:1 row_mask:0xf bank_mask:0xf
	v_fmac_f32_dpp v4, v124, v60 row_newbcast:2 row_mask:0xf bank_mask:0xf
	v_fmac_f32_dpp v5, v125, v60 row_newbcast:2 row_mask:0xf bank_mask:0xf
	v_fmac_f32_dpp v2, v126, v60 row_newbcast:2 row_mask:0xf bank_mask:0xf
	v_fmac_f32_dpp v3, v127, v60 row_newbcast:2 row_mask:0xf bank_mask:0xf
	v_fmac_f32_dpp v4, v124, v61 row_newbcast:3 row_mask:0xf bank_mask:0xf
	v_fmac_f32_dpp v5, v125, v61 row_newbcast:3 row_mask:0xf bank_mask:0xf
	v_fmac_f32_dpp v2, v126, v61 row_newbcast:3 row_mask:0xf bank_mask:0xf
	v_fmac_f32_dpp v3, v127, v61 row_newbcast:3 row_mask:0xf bank_mask:0xf
	v_fmac_f32_dpp v4, v124, v62 row_newbcast:4 row_mask:0xf bank_mask:0xf
	v_fmac_f32_dpp v5, v125, v62 row_newbcast:4 row_mask:0xf bank_mask:0xf
	v_fmac_f32_dpp v2, v126, v62 row_newbcast:4 row_mask:0xf bank_mask:0xf
	v_fmac_f32_dpp v3, v127, v62 row_newbcast:4 row_mask:0xf bank_mask:0xf
	v_fmac_f32_dpp v4, v124, v63 row_newbcast:5 row_mask:0xf bank_mask:0xf
	v_fmac_f32_dpp v5, v125, v63 row_newbcast:5 row_mask:0xf bank_mask:0xf
	v_fmac_f32_dpp v2, v126, v63 row_newbcast:5 row_mask:0xf bank_mask:0xf
	v_fmac_f32_dpp v3, v127, v63 row_newbcast:5 row_mask:0xf bank_mask:0xf
	v_fmac_f32_dpp v4, v124, v64 row_newbcast:6 row_mask:0xf bank_mask:0xf
	v_fmac_f32_dpp v5, v125, v64 row_newbcast:6 row_mask:0xf bank_mask:0xf
	v_fmac_f32_dpp v2, v126, v64 row_newbcast:6 row_mask:0xf bank_mask:0xf
	v_fmac_f32_dpp v3, v127, v64 row_newbcast:6 row_mask:0xf bank_mask:0xf
	v_fmac_f32_dpp v4, v124, v65 row_newbcast:7 row_mask:0xf bank_mask:0xf
	v_fmac_f32_dpp v5, v125, v65 row_newbcast:7 row_mask:0xf bank_mask:0xf
	v_fmac_f32_dpp v2, v126, v65 row_newbcast:7 row_mask:0xf bank_mask:0xf
	v_fmac_f32_dpp v3, v127, v65 row_newbcast:7 row_mask:0xf bank_mask:0xf
	v_fmac_f32_dpp v4, v124, v66 row_newbcast:8 row_mask:0xf bank_mask:0xf
	v_fmac_f32_dpp v5, v125, v66 row_newbcast:8 row_mask:0xf bank_mask:0xf
	v_fmac_f32_dpp v2, v126, v66 row_newbcast:8 row_mask:0xf bank_mask:0xf
	v_fmac_f32_dpp v3, v127, v66 row_newbcast:8 row_mask:0xf bank_mask:0xf
	v_fmac_f32_dpp v4, v124, v67 row_newbcast:9 row_mask:0xf bank_mask:0xf
	v_fmac_f32_dpp v5, v125, v67 row_newbcast:9 row_mask:0xf bank_mask:0xf
	v_fmac_f32_dpp v2, v126, v67 row_newbcast:9 row_mask:0xf bank_mask:0xf
	v_fmac_f32_dpp v3, v127, v67 row_newbcast:9 row_mask:0xf bank_mask:0xf
	v_fmac_f32_dpp v4, v124, v68 row_newbcast:10 row_mask:0xf bank_mask:0xf
	v_fmac_f32_dpp v5, v125, v68 row_newbcast:10 row_mask:0xf bank_mask:0xf
	v_fmac_f32_dpp v2, v126, v68 row_newbcast:10 row_mask:0xf bank_mask:0xf
	v_fmac_f32_dpp v3, v127, v68 row_newbcast:10 row_mask:0xf bank_mask:0xf
	v_fmac_f32_dpp v4, v124, v69 row_newbcast:11 row_mask:0xf bank_mask:0xf
	v_fmac_f32_dpp v5, v125, v69 row_newbcast:11 row_mask:0xf bank_mask:0xf
	v_fmac_f32_dpp v2, v126, v69 row_newbcast:11 row_mask:0xf bank_mask:0xf
	v_fmac_f32_dpp v3, v127, v69 row_newbcast:11 row_mask:0xf bank_mask:0xf
	v_fmac_f32_dpp v4, v124, v70 row_newbcast:12 row_mask:0xf bank_mask:0xf
	v_fmac_f32_dpp v5, v125, v70 row_newbcast:12 row_mask:0xf bank_mask:0xf
	v_fmac_f32_dpp v2, v126, v70 row_newbcast:12 row_mask:0xf bank_mask:0xf
	v_fmac_f32_dpp v3, v127, v70 row_newbcast:12 row_mask:0xf bank_mask:0xf
	v_fmac_f32_dpp v4, v124, v71 row_newbcast:13 row_mask:0xf bank_mask:0xf
	v_fmac_f32_dpp v5, v125, v71 row_newbcast:13 row_mask:0xf bank_mask:0xf
	v_fmac_f32_dpp v2, v126, v71 row_newbcast:13 row_mask:0xf bank_mask:0xf
	v_fmac_f32_dpp v3, v127, v71 row_newbcast:13 row_mask:0xf bank_mask:0xf
	v_fmac_f32_dpp v4, v124, v72 row_newbcast:14 row_mask:0xf bank_mask:0xf
	v_fmac_f32_dpp v5, v125, v72 row_newbcast:14 row_mask:0xf bank_mask:0xf
	v_fmac_f32_dpp v2, v126, v72 row_newbcast:14 row_mask:0xf bank_mask:0xf
	v_fmac_f32_dpp v3, v127, v72 row_newbcast:14 row_mask:0xf bank_mask:0xf
	v_fmac_f32_dpp v4, v124, v73 row_newbcast:15 row_mask:0xf bank_mask:0xf
	v_fmac_f32_dpp v5, v125, v73 row_newbcast:15 row_mask:0xf bank_mask:0xf
	v_fmac_f32_dpp v2, v126, v73 row_newbcast:15 row_mask:0xf bank_mask:0xf
	v_fmac_f32_dpp v3, v127, v73 row_newbcast:15 row_mask:0xf bank_mask:0xf
	s_waitcnt vmcnt(0)
	v_lshlrev_b32_e32 v128, 16, v128
	v_lshlrev_b32_e32 v129, 16, v129
	v_lshlrev_b32_e32 v130, 16, v130
	v_lshlrev_b32_e32 v131, 16, v131
	v_fmac_f32_dpp v4, v128, v74 row_newbcast:0 row_mask:0xf bank_mask:0xf
	v_fmac_f32_dpp v5, v129, v74 row_newbcast:0 row_mask:0xf bank_mask:0xf
	v_fmac_f32_dpp v2, v130, v74 row_newbcast:0 row_mask:0xf bank_mask:0xf
	v_fmac_f32_dpp v3, v131, v74 row_newbcast:0 row_mask:0xf bank_mask:0xf
	v_fmac_f32_dpp v4, v128, v75 row_newbcast:1 row_mask:0xf bank_mask:0xf
	v_fmac_f32_dpp v5, v129, v75 row_newbcast:1 row_mask:0xf bank_mask:0xf
	v_fmac_f32_dpp v2, v130, v75 row_newbcast:1 row_mask:0xf bank_mask:0xf
	v_fmac_f32_dpp v3, v131, v75 row_newbcast:1 row_mask:0xf bank_mask:0xf
	v_fmac_f32_dpp v4, v128, v76 row_newbcast:2 row_mask:0xf bank_mask:0xf
	v_fmac_f32_dpp v5, v129, v76 row_newbcast:2 row_mask:0xf bank_mask:0xf
	v_fmac_f32_dpp v2, v130, v76 row_newbcast:2 row_mask:0xf bank_mask:0xf
	v_fmac_f32_dpp v3, v131, v76 row_newbcast:2 row_mask:0xf bank_mask:0xf
	v_fmac_f32_dpp v4, v128, v77 row_newbcast:3 row_mask:0xf bank_mask:0xf
	v_fmac_f32_dpp v5, v129, v77 row_newbcast:3 row_mask:0xf bank_mask:0xf
	v_fmac_f32_dpp v2, v130, v77 row_newbcast:3 row_mask:0xf bank_mask:0xf
	v_fmac_f32_dpp v3, v131, v77 row_newbcast:3 row_mask:0xf bank_mask:0xf
	v_fmac_f32_dpp v4, v128, v78 row_newbcast:4 row_mask:0xf bank_mask:0xf
	v_fmac_f32_dpp v5, v129, v78 row_newbcast:4 row_mask:0xf bank_mask:0xf
	v_fmac_f32_dpp v2, v130, v78 row_newbcast:4 row_mask:0xf bank_mask:0xf
	v_fmac_f32_dpp v3, v131, v78 row_newbcast:4 row_mask:0xf bank_mask:0xf
	v_fmac_f32_dpp v4, v128, v79 row_newbcast:5 row_mask:0xf bank_mask:0xf
	v_fmac_f32_dpp v5, v129, v79 row_newbcast:5 row_mask:0xf bank_mask:0xf
	v_fmac_f32_dpp v2, v130, v79 row_newbcast:5 row_mask:0xf bank_mask:0xf
	v_fmac_f32_dpp v3, v131, v79 row_newbcast:5 row_mask:0xf bank_mask:0xf
	v_fmac_f32_dpp v4, v128, v80 row_newbcast:6 row_mask:0xf bank_mask:0xf
	v_fmac_f32_dpp v5, v129, v80 row_newbcast:6 row_mask:0xf bank_mask:0xf
	v_fmac_f32_dpp v2, v130, v80 row_newbcast:6 row_mask:0xf bank_mask:0xf
	v_fmac_f32_dpp v3, v131, v80 row_newbcast:6 row_mask:0xf bank_mask:0xf
	v_fmac_f32_dpp v4, v128, v81 row_newbcast:7 row_mask:0xf bank_mask:0xf
	v_fmac_f32_dpp v5, v129, v81 row_newbcast:7 row_mask:0xf bank_mask:0xf
	v_fmac_f32_dpp v2, v130, v81 row_newbcast:7 row_mask:0xf bank_mask:0xf
	v_fmac_f32_dpp v3, v131, v81 row_newbcast:7 row_mask:0xf bank_mask:0xf
	v_fmac_f32_dpp v4, v128, v82 row_newbcast:8 row_mask:0xf bank_mask:0xf
	v_fmac_f32_dpp v5, v129, v82 row_newbcast:8 row_mask:0xf bank_mask:0xf
	v_fmac_f32_dpp v2, v130, v82 row_newbcast:8 row_mask:0xf bank_mask:0xf
	v_fmac_f32_dpp v3, v131, v82 row_newbcast:8 row_mask:0xf bank_mask:0xf
	v_fmac_f32_dpp v4, v128, v83 row_newbcast:9 row_mask:0xf bank_mask:0xf
	v_fmac_f32_dpp v5, v129, v83 row_newbcast:9 row_mask:0xf bank_mask:0xf
	v_fmac_f32_dpp v2, v130, v83 row_newbcast:9 row_mask:0xf bank_mask:0xf
	v_fmac_f32_dpp v3, v131, v83 row_newbcast:9 row_mask:0xf bank_mask:0xf
	v_fmac_f32_dpp v4, v128, v84 row_newbcast:10 row_mask:0xf bank_mask:0xf
	v_fmac_f32_dpp v5, v129, v84 row_newbcast:10 row_mask:0xf bank_mask:0xf
	v_fmac_f32_dpp v2, v130, v84 row_newbcast:10 row_mask:0xf bank_mask:0xf
	v_fmac_f32_dpp v3, v131, v84 row_newbcast:10 row_mask:0xf bank_mask:0xf
	v_fmac_f32_dpp v4, v128, v85 row_newbcast:11 row_mask:0xf bank_mask:0xf
	v_fmac_f32_dpp v5, v129, v85 row_newbcast:11 row_mask:0xf bank_mask:0xf
	v_fmac_f32_dpp v2, v130, v85 row_newbcast:11 row_mask:0xf bank_mask:0xf
	v_fmac_f32_dpp v3, v131, v85 row_newbcast:11 row_mask:0xf bank_mask:0xf
	v_fmac_f32_dpp v4, v128, v86 row_newbcast:12 row_mask:0xf bank_mask:0xf
	v_fmac_f32_dpp v5, v129, v86 row_newbcast:12 row_mask:0xf bank_mask:0xf
	v_fmac_f32_dpp v2, v130, v86 row_newbcast:12 row_mask:0xf bank_mask:0xf
	v_fmac_f32_dpp v3, v131, v86 row_newbcast:12 row_mask:0xf bank_mask:0xf
	v_fmac_f32_dpp v4, v128, v87 row_newbcast:13 row_mask:0xf bank_mask:0xf
	v_fmac_f32_dpp v5, v129, v87 row_newbcast:13 row_mask:0xf bank_mask:0xf
	v_fmac_f32_dpp v2, v130, v87 row_newbcast:13 row_mask:0xf bank_mask:0xf
	v_fmac_f32_dpp v3, v131, v87 row_newbcast:13 row_mask:0xf bank_mask:0xf
	v_fmac_f32_dpp v4, v128, v88 row_newbcast:14 row_mask:0xf bank_mask:0xf
	v_fmac_f32_dpp v5, v129, v88 row_newbcast:14 row_mask:0xf bank_mask:0xf
	v_fmac_f32_dpp v2, v130, v88 row_newbcast:14 row_mask:0xf bank_mask:0xf
	v_fmac_f32_dpp v3, v131, v88 row_newbcast:14 row_mask:0xf bank_mask:0xf
	v_fmac_f32_dpp v4, v128, v89 row_newbcast:15 row_mask:0xf bank_mask:0xf
	v_fmac_f32_dpp v5, v129, v89 row_newbcast:15 row_mask:0xf bank_mask:0xf
	v_fmac_f32_dpp v2, v130, v89 row_newbcast:15 row_mask:0xf bank_mask:0xf
	v_fmac_f32_dpp v3, v131, v89 row_newbcast:15 row_mask:0xf bank_mask:0xf
	s_cmpk_gt_u32 s2, 0x3ff
	s_cselect_b64 s[16:17], -1, 0
	s_mov_b64 s[6:7], -1
	s_and_b64 vcc, exec, s[16:17]
	s_cbranch_vccz .LBB0_713
	v_cvt_pk_bf16_f32 v9, v4, v11
	s_mov_b64 s[6:7], 0
